# expert GEMM tile heads: next-tile range test as scalar compares instead of two 64-bit VALU compares
# speedup vs baseline: 1.0001x; 1.0001x over previous
.LBB0_1791:
	s_add_i32 s71, s71, 1
	s_mul_i32 s3, s71, s70
	s_mul_hi_u32 s24, s71, s19
	s_add_i32 s3, s24, s3
	s_mul_i32 s24, s71, s19
	s_add_u32 s24, s24, s2
	s_addc_u32 s25, s3, s73
	s_cmp_eq_u32 s25, 0
	s_cselect_b32 s3, s24, -1
	s_cmp_lt_u32 s3, 0x2800
	s_cselect_b64 s[38:39], exec, 0
	s_cselect_b64 s[40:41], 0, exec
	s_and_b64 vcc, exec, s[40:41]
	s_cbranch_vccnz .LBB0_1800
	s_and_b32 s3, s24, 7
	s_lshr_b32 s59, s24, 3
	s_mul_i32 s3, s3, 0x500
	s_add_i32 s3, s3, s59
	s_bfe_u32 s58, s3, 0x40003
	s_lshr_b32 s59, s3, 7
	s_lshl_b32 s59, s59, 3
	s_and_b32 s3, s3, 7
	s_add_i32 s60, s59, s3
	s_andn2_b64 vcc, exec, s[40:41]
	s_mov_b64 s[24:25], -1
	s_cbranch_vccz .LBB0_1801

.LBB0_1862:
	s_add_i32 s74, s74, 1
	s_mul_i32 s3, s74, s71
	s_mul_hi_u32 s36, s74, s19
	s_add_i32 s3, s36, s3
	s_mul_i32 s36, s74, s19
	s_add_u32 s36, s36, s2
	s_addc_u32 s37, s3, s73
	s_cmp_eq_u32 s37, 0
	s_cselect_b32 s3, s36, -1
	s_cmp_lt_u32 s3, 0xa00
	s_cselect_b64 s[40:41], exec, 0
	s_cselect_b64 vcc, 0, exec
	s_cbranch_vccnz .LBB0_1864
	s_and_b32 s3, s36, 7
	s_lshr_b32 s59, s36, 3
	s_mul_i32 s3, s3, 0x140
	s_add_i32 s3, s3, s59
	s_bfe_u32 s58, s3, 0x20003
	s_lshr_b32 s59, s3, 5
	s_lshl_b32 s59, s59, 3
	s_and_b32 s3, s3, 7
	s_add_i32 s60, s59, s3
	s_mul_i32 s98, s60, 0xcccd
	s_lshr_b32 s98, s98, 22
	s_mul_i32 s98, s98, 0xa0
	s_addk_i32 s98, 0x4f
	s_sub_i32 s60, s98, s60
